# phase 10: static s_setprio 1 for waves 0-3 (the waves that own the 9th token slot) instead of waves 4-7
# speedup vs baseline: 1.0031x; 1.0026x over previous
.LBB0_2035:
	s_cmp_lt_i32 s94, 11
	s_cselect_b64 s[2:3], -1, 0
	s_and_b64 s[0:1], s[2:3], s[0:1]
	s_andn2_b64 vcc, exec, s[0:1]
	s_cbranch_vccnz .LBB0_2059
	v_readfirstlane_b32 s98, v187
	s_cmp_ge_u32 s98, 4
	s_cbranch_scc1 .Lp10_noprio
	s_setprio 1
